# conv and pool LDS tile fills: all loads in flight then one wait (was load-wait-write serialized)
# speedup vs baseline: 1.0027x; 1.0027x over previous
; #define LAS __attribute__((address_space(3)))
; __global__ void __launch_bounds__(512, 2) fwd_megakernel(Params p_) {
;     ...
;                     const int R0 = rb * 128 + 32 * c; int base, S; seq_of_row(R0, base, S); const int t0 = R0 - base;
;                     __syncthreads();
; #pragma unroll
;                     for (int it = 0; it < 8; ++it) { const int idx = it * 512 + tid; if (idx < 62 * 64) { const int q = idx >> 6, c16 = idx & 63, tt = t0 - 15 + q;
;                         u32x4 v = {0u, 0u, 0u, 0u}; if (tt >= 0 && tt < S) v = *(const u32x4*)(H + SEG_C + (size_t)(base + tt) * LDC + c16 * 8);
;                         *(LAS u32x4*)(VT + q * 1024 + c16 * 16) = v; } }
.LBB0_319:
	s_lshl_b32 s31, s30, 7
	s_cmpk_lt_i32 s30, 0x80
	s_movk_i32 s3, 0xf800
	s_cselect_b32 s3, s3, 0x7fffe000
	s_movk_i32 s4, 0x800
	s_cselect_b32 s28, s4, 0x2000
	s_and_b32 s4, s3, s31
	s_add_i32 s3, s31, -15
	s_sub_i32 s29, s3, s4
	s_barrier
	s_mov_b64 s[4:5], exec
	s_and_b64 exec, s[4:5], s[10:11]
	v_add_u32_e32 v236, s29, v60
	v_cmp_gt_u32_e32 vcc, s28, v236
	v_mov_b32_e32 v200, 0
	v_mov_b32_e32 v201, 0
	v_mov_b32_e32 v202, 0
	v_mov_b32_e32 v203, 0
	s_and_b64 exec, exec, vcc
	v_add_u32_e32 v232, s3, v60
	v_ashrrev_i32_e32 v233, 31, v232
	v_lshlrev_b64 v[232:233], 11, v[232:233]
	v_lshl_add_u64 v[232:233], v[38:39], 0, v[232:233]
	global_load_dwordx4 v[200:203], v[232:233], off
	s_and_b64 exec, s[4:5], s[12:13]
	v_add_u32_e32 v236, s29, v62
	v_cmp_gt_u32_e32 vcc, s28, v236
	v_mov_b32_e32 v204, 0
	v_mov_b32_e32 v205, 0
	v_mov_b32_e32 v206, 0
	v_mov_b32_e32 v207, 0
	s_and_b64 exec, exec, vcc
	v_add_u32_e32 v234, s3, v62
	v_ashrrev_i32_e32 v235, 31, v234
	v_lshlrev_b64 v[234:235], 11, v[234:235]
	v_lshl_add_u64 v[234:235], v[38:39], 0, v[234:235]
	global_load_dwordx4 v[204:207], v[234:235], off
	s_and_b64 exec, s[4:5], s[14:15]
	v_add_u32_e32 v236, s29, v64
	v_cmp_gt_u32_e32 vcc, s28, v236
	v_mov_b32_e32 v208, 0
	v_mov_b32_e32 v209, 0
	v_mov_b32_e32 v210, 0
	v_mov_b32_e32 v211, 0
	s_and_b64 exec, exec, vcc
	v_add_u32_e32 v232, s3, v64
	v_ashrrev_i32_e32 v233, 31, v232
	v_lshlrev_b64 v[232:233], 11, v[232:233]
	v_lshl_add_u64 v[232:233], v[38:39], 0, v[232:233]
	global_load_dwordx4 v[208:211], v[232:233], off
	s_and_b64 exec, s[4:5], s[16:17]
	v_add_u32_e32 v236, s29, v66
	v_cmp_gt_u32_e32 vcc, s28, v236
	v_mov_b32_e32 v212, 0
	v_mov_b32_e32 v213, 0
	v_mov_b32_e32 v214, 0
	v_mov_b32_e32 v215, 0
	s_and_b64 exec, exec, vcc
	v_add_u32_e32 v234, s3, v66
	v_ashrrev_i32_e32 v235, 31, v234
	v_lshlrev_b64 v[234:235], 11, v[234:235]
	v_lshl_add_u64 v[234:235], v[38:39], 0, v[234:235]
	global_load_dwordx4 v[212:215], v[234:235], off
	s_and_b64 exec, s[4:5], s[18:19]
	v_add_u32_e32 v236, s29, v68
	v_cmp_gt_u32_e32 vcc, s28, v236
	v_mov_b32_e32 v216, 0
	v_mov_b32_e32 v217, 0
	v_mov_b32_e32 v218, 0
	v_mov_b32_e32 v219, 0
	s_and_b64 exec, exec, vcc
	v_add_u32_e32 v232, s3, v68
	v_ashrrev_i32_e32 v233, 31, v232
	v_lshlrev_b64 v[232:233], 11, v[232:233]
	v_lshl_add_u64 v[232:233], v[38:39], 0, v[232:233]
	global_load_dwordx4 v[216:219], v[232:233], off
	s_and_b64 exec, s[4:5], s[20:21]
	v_add_u32_e32 v236, s29, v70
	v_cmp_gt_u32_e32 vcc, s28, v236
	v_mov_b32_e32 v220, 0
	v_mov_b32_e32 v221, 0
	v_mov_b32_e32 v222, 0
	v_mov_b32_e32 v223, 0
	s_and_b64 exec, exec, vcc
	v_add_u32_e32 v234, s3, v70
	v_ashrrev_i32_e32 v235, 31, v234
	v_lshlrev_b64 v[234:235], 11, v[234:235]
	v_lshl_add_u64 v[234:235], v[38:39], 0, v[234:235]
	global_load_dwordx4 v[220:223], v[234:235], off
	s_and_b64 exec, s[4:5], s[22:23]
	v_add_u32_e32 v236, s29, v72
	v_cmp_gt_u32_e32 vcc, s28, v236
	v_mov_b32_e32 v224, 0
	v_mov_b32_e32 v225, 0
	v_mov_b32_e32 v226, 0
	v_mov_b32_e32 v227, 0
	s_and_b64 exec, exec, vcc
	v_add_u32_e32 v232, s3, v72
	v_ashrrev_i32_e32 v233, 31, v232
	v_lshlrev_b64 v[232:233], 11, v[232:233]
	v_lshl_add_u64 v[232:233], v[38:39], 0, v[232:233]
	global_load_dwordx4 v[224:227], v[232:233], off
	s_and_b64 exec, s[4:5], s[24:25]
	v_add_u32_e32 v236, s29, v74
	v_cmp_gt_u32_e32 vcc, s28, v236
	v_mov_b32_e32 v228, 0
	v_mov_b32_e32 v229, 0
	v_mov_b32_e32 v230, 0
	v_mov_b32_e32 v231, 0
	s_and_b64 exec, exec, vcc
	v_add_u32_e32 v234, s3, v74
	v_ashrrev_i32_e32 v235, 31, v234
	v_lshlrev_b64 v[234:235], 11, v[234:235]
	v_lshl_add_u64 v[234:235], v[38:39], 0, v[234:235]
	global_load_dwordx4 v[228:231], v[234:235], off
	s_mov_b64 exec, s[4:5]
	v_add_u32_e32 v237, v59, v61
	v_add_u32_e32 v238, v59, v63
	v_add_u32_e32 v239, v59, v65
	v_add_u32_e32 v240, v59, v67
	v_add_u32_e32 v241, v59, v69
	v_add_u32_e32 v242, v59, v71
	v_add_u32_e32 v243, v59, v73
	v_add_u32_e32 v244, v59, v75
	s_waitcnt vmcnt(0)
	s_and_b64 exec, s[4:5], s[10:11]
	ds_write_b128 v237, v[200:203] offset:63488
	s_and_b64 exec, s[4:5], s[12:13]
	ds_write_b128 v238, v[204:207] offset:63488
	s_and_b64 exec, s[4:5], s[14:15]
	ds_write_b128 v239, v[208:211] offset:63488
	s_and_b64 exec, s[4:5], s[16:17]
	ds_write_b128 v240, v[212:215] offset:63488
	s_and_b64 exec, s[4:5], s[18:19]
	ds_write_b128 v241, v[216:219] offset:63488
	s_and_b64 exec, s[4:5], s[20:21]
	ds_write_b128 v242, v[220:223] offset:63488
	s_and_b64 exec, s[4:5], s[22:23]
	ds_write_b128 v243, v[224:227] offset:63488
	s_and_b64 exec, s[4:5], s[24:25]
	ds_write_b128 v244, v[228:231] offset:63488

; #define LAS __attribute__((address_space(3)))
; __global__ void __launch_bounds__(512, 2) fwd_megakernel(Params p_) {
;     ...
;                     const int R0 = rb * 128 + 32 * c; int base, S; seq_of_row(R0, base, S); const int t0 = R0 - base;
;                     __syncthreads();
; #pragma unroll
;                     for (int it = 0; it < 8; ++it) { const int idx = it * 512 + tid; if (idx < 62 * 64) { const int q = idx >> 6, c16 = idx & 63, tt = t0 - 15 + q;
;                         u32x4 v = {0u, 0u, 0u, 0u}; if (tt >= 0 && tt < S) v = *(const u32x4*)(H + SEG_C + (size_t)(base + tt) * LDC + c16 * 8);
;                         *(LAS u32x4*)(VT + q * 1024 + c16 * 16) = v; } }
.LBB0_358:
	s_or_b32 s3, s31, 32
	s_cmpk_lt_i32 s3, 0x4000
	s_movk_i32 s4, 0xf800
	s_cselect_b32 s4, s4, 0x7fffe000
	s_movk_i32 s5, 0x800
	s_cselect_b32 s29, s5, 0x2000
	s_and_b32 s4, s4, s31
	s_or_b32 s28, s31, 17
	s_sub_i32 s36, s28, s4
	s_barrier
	s_mov_b64 s[4:5], exec
	s_and_b64 exec, s[4:5], s[10:11]
	v_add_u32_e32 v236, s36, v60
	v_cmp_gt_u32_e32 vcc, s29, v236
	v_mov_b32_e32 v200, 0
	v_mov_b32_e32 v201, 0
	v_mov_b32_e32 v202, 0
	v_mov_b32_e32 v203, 0
	s_and_b64 exec, exec, vcc
	v_add_u32_e32 v232, s28, v60
	v_ashrrev_i32_e32 v233, 31, v232
	v_lshlrev_b64 v[232:233], 11, v[232:233]
	v_lshl_add_u64 v[232:233], v[38:39], 0, v[232:233]
	global_load_dwordx4 v[200:203], v[232:233], off
	s_and_b64 exec, s[4:5], s[12:13]
	v_add_u32_e32 v236, s36, v62
	v_cmp_gt_u32_e32 vcc, s29, v236
	v_mov_b32_e32 v204, 0
	v_mov_b32_e32 v205, 0
	v_mov_b32_e32 v206, 0
	v_mov_b32_e32 v207, 0
	s_and_b64 exec, exec, vcc
	v_add_u32_e32 v234, s28, v62
	v_ashrrev_i32_e32 v235, 31, v234
	v_lshlrev_b64 v[234:235], 11, v[234:235]
	v_lshl_add_u64 v[234:235], v[38:39], 0, v[234:235]
	global_load_dwordx4 v[204:207], v[234:235], off
	s_and_b64 exec, s[4:5], s[14:15]
	v_add_u32_e32 v236, s36, v64
	v_cmp_gt_u32_e32 vcc, s29, v236
	v_mov_b32_e32 v208, 0
	v_mov_b32_e32 v209, 0
	v_mov_b32_e32 v210, 0
	v_mov_b32_e32 v211, 0
	s_and_b64 exec, exec, vcc
	v_add_u32_e32 v232, s28, v64
	v_ashrrev_i32_e32 v233, 31, v232
	v_lshlrev_b64 v[232:233], 11, v[232:233]
	v_lshl_add_u64 v[232:233], v[38:39], 0, v[232:233]
	global_load_dwordx4 v[208:211], v[232:233], off
	s_and_b64 exec, s[4:5], s[16:17]
	v_add_u32_e32 v236, s36, v66
	v_cmp_gt_u32_e32 vcc, s29, v236
	v_mov_b32_e32 v212, 0
	v_mov_b32_e32 v213, 0
	v_mov_b32_e32 v214, 0
	v_mov_b32_e32 v215, 0
	s_and_b64 exec, exec, vcc
	v_add_u32_e32 v234, s28, v66
	v_ashrrev_i32_e32 v235, 31, v234
	v_lshlrev_b64 v[234:235], 11, v[234:235]
	v_lshl_add_u64 v[234:235], v[38:39], 0, v[234:235]
	global_load_dwordx4 v[212:215], v[234:235], off
	s_and_b64 exec, s[4:5], s[18:19]
	v_add_u32_e32 v236, s36, v68
	v_cmp_gt_u32_e32 vcc, s29, v236
	v_mov_b32_e32 v216, 0
	v_mov_b32_e32 v217, 0
	v_mov_b32_e32 v218, 0
	v_mov_b32_e32 v219, 0
	s_and_b64 exec, exec, vcc
	v_add_u32_e32 v232, s28, v68
	v_ashrrev_i32_e32 v233, 31, v232
	v_lshlrev_b64 v[232:233], 11, v[232:233]
	v_lshl_add_u64 v[232:233], v[38:39], 0, v[232:233]
	global_load_dwordx4 v[216:219], v[232:233], off
	s_and_b64 exec, s[4:5], s[20:21]
	v_add_u32_e32 v236, s36, v70
	v_cmp_gt_u32_e32 vcc, s29, v236
	v_mov_b32_e32 v220, 0
	v_mov_b32_e32 v221, 0
	v_mov_b32_e32 v222, 0
	v_mov_b32_e32 v223, 0
	s_and_b64 exec, exec, vcc
	v_add_u32_e32 v234, s28, v70
	v_ashrrev_i32_e32 v235, 31, v234
	v_lshlrev_b64 v[234:235], 11, v[234:235]
	v_lshl_add_u64 v[234:235], v[38:39], 0, v[234:235]
	global_load_dwordx4 v[220:223], v[234:235], off
	s_and_b64 exec, s[4:5], s[22:23]
	v_add_u32_e32 v236, s36, v72
	v_cmp_gt_u32_e32 vcc, s29, v236
	v_mov_b32_e32 v224, 0
	v_mov_b32_e32 v225, 0
	v_mov_b32_e32 v226, 0
	v_mov_b32_e32 v227, 0
	s_and_b64 exec, exec, vcc
	v_add_u32_e32 v232, s28, v72
	v_ashrrev_i32_e32 v233, 31, v232
	v_lshlrev_b64 v[232:233], 11, v[232:233]
	v_lshl_add_u64 v[232:233], v[38:39], 0, v[232:233]
	global_load_dwordx4 v[224:227], v[232:233], off
	s_and_b64 exec, s[4:5], s[24:25]
	v_add_u32_e32 v236, s36, v74
	v_cmp_gt_u32_e32 vcc, s29, v236
	v_mov_b32_e32 v228, 0
	v_mov_b32_e32 v229, 0
	v_mov_b32_e32 v230, 0
	v_mov_b32_e32 v231, 0
	s_and_b64 exec, exec, vcc
	v_add_u32_e32 v234, s28, v74
	v_ashrrev_i32_e32 v235, 31, v234
	v_lshlrev_b64 v[234:235], 11, v[234:235]
	v_lshl_add_u64 v[234:235], v[38:39], 0, v[234:235]
	global_load_dwordx4 v[228:231], v[234:235], off
	s_mov_b64 exec, s[4:5]
	v_add_u32_e32 v237, v59, v61
	v_add_u32_e32 v238, v59, v63
	v_add_u32_e32 v239, v59, v65
	v_add_u32_e32 v240, v59, v67
	v_add_u32_e32 v241, v59, v69
	v_add_u32_e32 v242, v59, v71
	v_add_u32_e32 v243, v59, v73
	v_add_u32_e32 v244, v59, v75
	s_waitcnt vmcnt(0)
	s_and_b64 exec, s[4:5], s[10:11]
	ds_write_b128 v237, v[200:203] offset:63488
	s_and_b64 exec, s[4:5], s[12:13]
	ds_write_b128 v238, v[204:207] offset:63488
	s_and_b64 exec, s[4:5], s[14:15]
	ds_write_b128 v239, v[208:211] offset:63488
	s_and_b64 exec, s[4:5], s[16:17]
	ds_write_b128 v240, v[212:215] offset:63488
	s_and_b64 exec, s[4:5], s[18:19]
	ds_write_b128 v241, v[216:219] offset:63488
	s_and_b64 exec, s[4:5], s[20:21]
	ds_write_b128 v242, v[220:223] offset:63488
	s_and_b64 exec, s[4:5], s[22:23]
	ds_write_b128 v243, v[224:227] offset:63488
	s_and_b64 exec, s[4:5], s[24:25]
	ds_write_b128 v244, v[228:231] offset:63488

; #define LAS __attribute__((address_space(3)))
; __global__ void __launch_bounds__(512, 2) fwd_megakernel(Params p_) {
;     ...
;                     const int R0 = rb * 128 + 32 * c; int base, S; seq_of_row(R0, base, S); const int t0 = R0 - base;
;                     __syncthreads();
; #pragma unroll
;                     for (int it = 0; it < 8; ++it) { const int idx = it * 512 + tid; if (idx < 62 * 64) { const int q = idx >> 6, c16 = idx & 63, tt = t0 - 15 + q;
;                         u32x4 v = {0u, 0u, 0u, 0u}; if (tt >= 0 && tt < S) v = *(const u32x4*)(H + SEG_C + (size_t)(base + tt) * LDC + c16 * 8);
;                         *(LAS u32x4*)(VT + q * 1024 + c16 * 16) = v; } }
.LBB0_397:
	s_or_b32 s3, s31, 64
	s_cmpk_lt_i32 s3, 0x4000
	s_movk_i32 s4, 0xf800
	s_cselect_b32 s4, s4, 0x7fffe000
	s_movk_i32 s5, 0x800
	s_cselect_b32 s37, s5, 0x2000
	s_and_b32 s4, s4, s31
	s_or_b32 s36, s31, 49
	s_sub_i32 s38, s36, s4
	s_barrier
	s_mov_b64 s[4:5], exec
	s_and_b64 exec, s[4:5], s[10:11]
	v_add_u32_e32 v236, s38, v60
	v_cmp_gt_u32_e32 vcc, s37, v236
	v_mov_b32_e32 v200, 0
	v_mov_b32_e32 v201, 0
	v_mov_b32_e32 v202, 0
	v_mov_b32_e32 v203, 0
	s_and_b64 exec, exec, vcc
	v_add_u32_e32 v232, s36, v60
	v_ashrrev_i32_e32 v233, 31, v232
	v_lshlrev_b64 v[232:233], 11, v[232:233]
	v_lshl_add_u64 v[232:233], v[38:39], 0, v[232:233]
	global_load_dwordx4 v[200:203], v[232:233], off
	s_and_b64 exec, s[4:5], s[12:13]
	v_add_u32_e32 v236, s38, v62
	v_cmp_gt_u32_e32 vcc, s37, v236
	v_mov_b32_e32 v204, 0
	v_mov_b32_e32 v205, 0
	v_mov_b32_e32 v206, 0
	v_mov_b32_e32 v207, 0
	s_and_b64 exec, exec, vcc
	v_add_u32_e32 v234, s36, v62
	v_ashrrev_i32_e32 v235, 31, v234
	v_lshlrev_b64 v[234:235], 11, v[234:235]
	v_lshl_add_u64 v[234:235], v[38:39], 0, v[234:235]
	global_load_dwordx4 v[204:207], v[234:235], off
	s_and_b64 exec, s[4:5], s[14:15]
	v_add_u32_e32 v236, s38, v64
	v_cmp_gt_u32_e32 vcc, s37, v236
	v_mov_b32_e32 v208, 0
	v_mov_b32_e32 v209, 0
	v_mov_b32_e32 v210, 0
	v_mov_b32_e32 v211, 0
	s_and_b64 exec, exec, vcc
	v_add_u32_e32 v232, s36, v64
	v_ashrrev_i32_e32 v233, 31, v232
	v_lshlrev_b64 v[232:233], 11, v[232:233]
	v_lshl_add_u64 v[232:233], v[38:39], 0, v[232:233]
	global_load_dwordx4 v[208:211], v[232:233], off
	s_and_b64 exec, s[4:5], s[16:17]
	v_add_u32_e32 v236, s38, v66
	v_cmp_gt_u32_e32 vcc, s37, v236
	v_mov_b32_e32 v212, 0
	v_mov_b32_e32 v213, 0
	v_mov_b32_e32 v214, 0
	v_mov_b32_e32 v215, 0
	s_and_b64 exec, exec, vcc
	v_add_u32_e32 v234, s36, v66
	v_ashrrev_i32_e32 v235, 31, v234
	v_lshlrev_b64 v[234:235], 11, v[234:235]
	v_lshl_add_u64 v[234:235], v[38:39], 0, v[234:235]
	global_load_dwordx4 v[212:215], v[234:235], off
	s_and_b64 exec, s[4:5], s[18:19]
	v_add_u32_e32 v236, s38, v68
	v_cmp_gt_u32_e32 vcc, s37, v236
	v_mov_b32_e32 v216, 0
	v_mov_b32_e32 v217, 0
	v_mov_b32_e32 v218, 0
	v_mov_b32_e32 v219, 0
	s_and_b64 exec, exec, vcc
	v_add_u32_e32 v232, s36, v68
	v_ashrrev_i32_e32 v233, 31, v232
	v_lshlrev_b64 v[232:233], 11, v[232:233]
	v_lshl_add_u64 v[232:233], v[38:39], 0, v[232:233]
	global_load_dwordx4 v[216:219], v[232:233], off
	s_and_b64 exec, s[4:5], s[20:21]
	v_add_u32_e32 v236, s38, v70
	v_cmp_gt_u32_e32 vcc, s37, v236
	v_mov_b32_e32 v220, 0
	v_mov_b32_e32 v221, 0
	v_mov_b32_e32 v222, 0
	v_mov_b32_e32 v223, 0
	s_and_b64 exec, exec, vcc
	v_add_u32_e32 v234, s36, v70
	v_ashrrev_i32_e32 v235, 31, v234
	v_lshlrev_b64 v[234:235], 11, v[234:235]
	v_lshl_add_u64 v[234:235], v[38:39], 0, v[234:235]
	global_load_dwordx4 v[220:223], v[234:235], off
	s_and_b64 exec, s[4:5], s[22:23]
	v_add_u32_e32 v236, s38, v72
	v_cmp_gt_u32_e32 vcc, s37, v236
	v_mov_b32_e32 v224, 0
	v_mov_b32_e32 v225, 0
	v_mov_b32_e32 v226, 0
	v_mov_b32_e32 v227, 0
	s_and_b64 exec, exec, vcc
	v_add_u32_e32 v232, s36, v72
	v_ashrrev_i32_e32 v233, 31, v232
	v_lshlrev_b64 v[232:233], 11, v[232:233]
	v_lshl_add_u64 v[232:233], v[38:39], 0, v[232:233]
	global_load_dwordx4 v[224:227], v[232:233], off
	s_and_b64 exec, s[4:5], s[24:25]
	v_add_u32_e32 v236, s38, v74
	v_cmp_gt_u32_e32 vcc, s37, v236
	v_mov_b32_e32 v228, 0
	v_mov_b32_e32 v229, 0
	v_mov_b32_e32 v230, 0
	v_mov_b32_e32 v231, 0
	s_and_b64 exec, exec, vcc
	v_add_u32_e32 v234, s36, v74
	v_ashrrev_i32_e32 v235, 31, v234
	v_lshlrev_b64 v[234:235], 11, v[234:235]
	v_lshl_add_u64 v[234:235], v[38:39], 0, v[234:235]
	global_load_dwordx4 v[228:231], v[234:235], off
	s_mov_b64 exec, s[4:5]
	v_add_u32_e32 v237, v59, v61
	v_add_u32_e32 v238, v59, v63
	v_add_u32_e32 v239, v59, v65
	v_add_u32_e32 v240, v59, v67
	v_add_u32_e32 v241, v59, v69
	v_add_u32_e32 v242, v59, v71
	v_add_u32_e32 v243, v59, v73
	v_add_u32_e32 v244, v59, v75
	s_waitcnt vmcnt(0)
	s_and_b64 exec, s[4:5], s[10:11]
	ds_write_b128 v237, v[200:203] offset:63488
	s_and_b64 exec, s[4:5], s[12:13]
	ds_write_b128 v238, v[204:207] offset:63488
	s_and_b64 exec, s[4:5], s[14:15]
	ds_write_b128 v239, v[208:211] offset:63488
	s_and_b64 exec, s[4:5], s[16:17]
	ds_write_b128 v240, v[212:215] offset:63488
	s_and_b64 exec, s[4:5], s[18:19]
	ds_write_b128 v241, v[216:219] offset:63488
	s_and_b64 exec, s[4:5], s[20:21]
	ds_write_b128 v242, v[220:223] offset:63488
	s_and_b64 exec, s[4:5], s[22:23]
	ds_write_b128 v243, v[224:227] offset:63488
	s_and_b64 exec, s[4:5], s[24:25]
	ds_write_b128 v244, v[228:231] offset:63488

; #define LAS __attribute__((address_space(3)))
; __global__ void __launch_bounds__(512, 2) fwd_megakernel(Params p_) {
;     ...
;                     const int R0 = rb * 128 + 32 * c; int base, S; seq_of_row(R0, base, S); const int t0 = R0 - base;
;                     __syncthreads();
; #pragma unroll
;                     for (int it = 0; it < 8; ++it) { const int idx = it * 512 + tid; if (idx < 62 * 64) { const int q = idx >> 6, c16 = idx & 63, tt = t0 - 15 + q;
;                         u32x4 v = {0u, 0u, 0u, 0u}; if (tt >= 0 && tt < S) v = *(const u32x4*)(H + SEG_C + (size_t)(base + tt) * LDC + c16 * 8);
;                         *(LAS u32x4*)(VT + q * 1024 + c16 * 16) = v; } }
.LBB0_436:
	s_or_b32 s3, s31, 0x60
	s_cmpk_lt_i32 s3, 0x4000
	s_movk_i32 s4, 0xf800
	s_cselect_b32 s4, s4, 0x7fffe000
	s_movk_i32 s5, 0x800
	s_cselect_b32 s36, s5, 0x2000
	s_and_b32 s4, s4, s31
	s_or_b32 s31, s31, 0x51
	s_sub_i32 s37, s31, s4
	s_barrier
	s_mov_b64 s[4:5], exec
	s_and_b64 exec, s[4:5], s[10:11]
	v_add_u32_e32 v236, s37, v60
	v_cmp_gt_u32_e32 vcc, s36, v236
	v_mov_b32_e32 v200, 0
	v_mov_b32_e32 v201, 0
	v_mov_b32_e32 v202, 0
	v_mov_b32_e32 v203, 0
	s_and_b64 exec, exec, vcc
	v_add_u32_e32 v232, s31, v60
	v_ashrrev_i32_e32 v233, 31, v232
	v_lshlrev_b64 v[232:233], 11, v[232:233]
	v_lshl_add_u64 v[232:233], v[38:39], 0, v[232:233]
	global_load_dwordx4 v[200:203], v[232:233], off
	s_and_b64 exec, s[4:5], s[12:13]
	v_add_u32_e32 v236, s37, v62
	v_cmp_gt_u32_e32 vcc, s36, v236
	v_mov_b32_e32 v204, 0
	v_mov_b32_e32 v205, 0
	v_mov_b32_e32 v206, 0
	v_mov_b32_e32 v207, 0
	s_and_b64 exec, exec, vcc
	v_add_u32_e32 v234, s31, v62
	v_ashrrev_i32_e32 v235, 31, v234
	v_lshlrev_b64 v[234:235], 11, v[234:235]
	v_lshl_add_u64 v[234:235], v[38:39], 0, v[234:235]
	global_load_dwordx4 v[204:207], v[234:235], off
	s_and_b64 exec, s[4:5], s[14:15]
	v_add_u32_e32 v236, s37, v64
	v_cmp_gt_u32_e32 vcc, s36, v236
	v_mov_b32_e32 v208, 0
	v_mov_b32_e32 v209, 0
	v_mov_b32_e32 v210, 0
	v_mov_b32_e32 v211, 0
	s_and_b64 exec, exec, vcc
	v_add_u32_e32 v232, s31, v64
	v_ashrrev_i32_e32 v233, 31, v232
	v_lshlrev_b64 v[232:233], 11, v[232:233]
	v_lshl_add_u64 v[232:233], v[38:39], 0, v[232:233]
	global_load_dwordx4 v[208:211], v[232:233], off
	s_and_b64 exec, s[4:5], s[16:17]
	v_add_u32_e32 v236, s37, v66
	v_cmp_gt_u32_e32 vcc, s36, v236
	v_mov_b32_e32 v212, 0
	v_mov_b32_e32 v213, 0
	v_mov_b32_e32 v214, 0
	v_mov_b32_e32 v215, 0
	s_and_b64 exec, exec, vcc
	v_add_u32_e32 v234, s31, v66
	v_ashrrev_i32_e32 v235, 31, v234
	v_lshlrev_b64 v[234:235], 11, v[234:235]
	v_lshl_add_u64 v[234:235], v[38:39], 0, v[234:235]
	global_load_dwordx4 v[212:215], v[234:235], off
	s_and_b64 exec, s[4:5], s[18:19]
	v_add_u32_e32 v236, s37, v68
	v_cmp_gt_u32_e32 vcc, s36, v236
	v_mov_b32_e32 v216, 0
	v_mov_b32_e32 v217, 0
	v_mov_b32_e32 v218, 0
	v_mov_b32_e32 v219, 0
	s_and_b64 exec, exec, vcc
	v_add_u32_e32 v232, s31, v68
	v_ashrrev_i32_e32 v233, 31, v232
	v_lshlrev_b64 v[232:233], 11, v[232:233]
	v_lshl_add_u64 v[232:233], v[38:39], 0, v[232:233]
	global_load_dwordx4 v[216:219], v[232:233], off
	s_and_b64 exec, s[4:5], s[20:21]
	v_add_u32_e32 v236, s37, v70
	v_cmp_gt_u32_e32 vcc, s36, v236
	v_mov_b32_e32 v220, 0
	v_mov_b32_e32 v221, 0
	v_mov_b32_e32 v222, 0
	v_mov_b32_e32 v223, 0
	s_and_b64 exec, exec, vcc
	v_add_u32_e32 v234, s31, v70
	v_ashrrev_i32_e32 v235, 31, v234
	v_lshlrev_b64 v[234:235], 11, v[234:235]
	v_lshl_add_u64 v[234:235], v[38:39], 0, v[234:235]
	global_load_dwordx4 v[220:223], v[234:235], off
	s_and_b64 exec, s[4:5], s[22:23]
	v_add_u32_e32 v236, s37, v72
	v_cmp_gt_u32_e32 vcc, s36, v236
	v_mov_b32_e32 v224, 0
	v_mov_b32_e32 v225, 0
	v_mov_b32_e32 v226, 0
	v_mov_b32_e32 v227, 0
	s_and_b64 exec, exec, vcc
	v_add_u32_e32 v232, s31, v72
	v_ashrrev_i32_e32 v233, 31, v232
	v_lshlrev_b64 v[232:233], 11, v[232:233]
	v_lshl_add_u64 v[232:233], v[38:39], 0, v[232:233]
	global_load_dwordx4 v[224:227], v[232:233], off
	s_and_b64 exec, s[4:5], s[24:25]
	v_add_u32_e32 v236, s37, v74
	v_cmp_gt_u32_e32 vcc, s36, v236
	v_mov_b32_e32 v228, 0
	v_mov_b32_e32 v229, 0
	v_mov_b32_e32 v230, 0
	v_mov_b32_e32 v231, 0
	s_and_b64 exec, exec, vcc
	v_add_u32_e32 v234, s31, v74
	v_ashrrev_i32_e32 v235, 31, v234
	v_lshlrev_b64 v[234:235], 11, v[234:235]
	v_lshl_add_u64 v[234:235], v[38:39], 0, v[234:235]
	global_load_dwordx4 v[228:231], v[234:235], off
	s_mov_b64 exec, s[4:5]
	v_add_u32_e32 v237, v59, v61
	v_add_u32_e32 v238, v59, v63
	v_add_u32_e32 v239, v59, v65
	v_add_u32_e32 v240, v59, v67
	v_add_u32_e32 v241, v59, v69
	v_add_u32_e32 v242, v59, v71
	v_add_u32_e32 v243, v59, v73
	v_add_u32_e32 v244, v59, v75
	s_waitcnt vmcnt(0)
	s_and_b64 exec, s[4:5], s[10:11]
	ds_write_b128 v237, v[200:203] offset:63488
	s_and_b64 exec, s[4:5], s[12:13]
	ds_write_b128 v238, v[204:207] offset:63488
	s_and_b64 exec, s[4:5], s[14:15]
	ds_write_b128 v239, v[208:211] offset:63488
	s_and_b64 exec, s[4:5], s[16:17]
	ds_write_b128 v240, v[212:215] offset:63488
	s_and_b64 exec, s[4:5], s[18:19]
	ds_write_b128 v241, v[216:219] offset:63488
	s_and_b64 exec, s[4:5], s[20:21]
	ds_write_b128 v242, v[220:223] offset:63488
	s_and_b64 exec, s[4:5], s[22:23]
	ds_write_b128 v243, v[224:227] offset:63488
	s_and_b64 exec, s[4:5], s[24:25]
	ds_write_b128 v244, v[228:231] offset:63488

; #define LAS __attribute__((address_space(3)))
; __global__ void __launch_bounds__(512, 2) fwd_megakernel(Params p_) {
;     ...
;                     const int hw = 1 << g, NR = 128 + 2 * hw;
;                     __syncthreads();
;                     for (int idx = tid; idx < NR * 32; idx += 512) { const int q = idx >> 5, c16 = idx & 31, tt = t0 - hw + q;
;                         u32x4 v = {0u, 0u, 0u, 0u}; if (tt >= 0 && tt < S) v = *(const u32x4*)(H + SEG_P + (size_t)(base + tt) * LDP + g * 256 + c16 * 8);
;                         *(LAS u32x4*)(lds + q * 512 + c16 * 16) = v; }
;                     __syncthreads();
.LBB0_478:
	s_lshl_b32 s22, 64, s20
	s_addk_i32 s22, 0x1000
	v_cmp_le_i32_e32 vcc, s22, v48
	s_barrier
	s_and_saveexec_b64 s[4:5], vcc
	s_xor_b64 s[4:5], exec, s[4:5]
	s_lshl_b32 s14, s20, 8
	s_or_saveexec_b64 s[4:5], s[4:5]
	s_lshl_b32 s21, 1, s20
	v_mov_b32_e32 v0, s14
	s_xor_b64 exec, exec, s[4:5]
	s_cbranch_execz .LBB0_486
	s_lshl_b32 s72, s20, 9
	s_sub_i32 s24, s19, s21
	s_lshl_b32 s23, s20, 8
	v_lshl_add_u64 v[4:5], v[50:51], 0, s[72:73]
	s_mov_b64 s[14:15], exec
	v_ashrrev_i32_e32 v6, 5, v48
	s_add_i32 s22, s22, 0xfffff000
	v_cmp_gt_i32_e64 s[16:17], s22, v48
	v_add_u32_e32 v241, 0, v6
	v_add_u32_e32 v240, s24, v241
	v_cmp_gt_u32_e32 vcc, s3, v240
	v_mov_b32_e32 v200, 0
	v_mov_b32_e32 v201, 0
	v_mov_b32_e32 v202, 0
	v_mov_b32_e32 v203, 0
	s_and_b64 exec, exec, vcc
	v_add_u32_e32 v236, s18, v240
	v_ashrrev_i32_e32 v237, 31, v236
	v_lshlrev_b64 v[236:237], 12, v[236:237]
	v_lshl_add_u64 v[236:237], v[4:5], 0, v[236:237]
	global_load_dwordx4 v[200:203], v[236:237], off
	s_mov_b64 exec, s[14:15]
	v_lshl_add_u32 v120, v241, 9, v78
	v_add_u32_e32 v241, 16, v6
	v_add_u32_e32 v240, s24, v241
	v_cmp_gt_u32_e32 vcc, s3, v240
	v_mov_b32_e32 v204, 0
	v_mov_b32_e32 v205, 0
	v_mov_b32_e32 v206, 0
	v_mov_b32_e32 v207, 0
	s_and_b64 exec, exec, vcc
	v_add_u32_e32 v238, s18, v240
	v_ashrrev_i32_e32 v239, 31, v238
	v_lshlrev_b64 v[238:239], 12, v[238:239]
	v_lshl_add_u64 v[238:239], v[4:5], 0, v[238:239]
	global_load_dwordx4 v[204:207], v[238:239], off
	s_mov_b64 exec, s[14:15]
	v_lshl_add_u32 v121, v241, 9, v78
	v_add_u32_e32 v241, 32, v6
	v_add_u32_e32 v240, s24, v241
	v_cmp_gt_u32_e32 vcc, s3, v240
	v_mov_b32_e32 v208, 0
	v_mov_b32_e32 v209, 0
	v_mov_b32_e32 v210, 0
	v_mov_b32_e32 v211, 0
	s_and_b64 exec, exec, vcc
	v_add_u32_e32 v236, s18, v240
	v_ashrrev_i32_e32 v237, 31, v236
	v_lshlrev_b64 v[236:237], 12, v[236:237]
	v_lshl_add_u64 v[236:237], v[4:5], 0, v[236:237]
	global_load_dwordx4 v[208:211], v[236:237], off
	s_mov_b64 exec, s[14:15]
	v_lshl_add_u32 v122, v241, 9, v78
	v_add_u32_e32 v241, 48, v6
	v_add_u32_e32 v240, s24, v241
	v_cmp_gt_u32_e32 vcc, s3, v240
	v_mov_b32_e32 v212, 0
	v_mov_b32_e32 v213, 0
	v_mov_b32_e32 v214, 0
	v_mov_b32_e32 v215, 0
	s_and_b64 exec, exec, vcc
	v_add_u32_e32 v238, s18, v240
	v_ashrrev_i32_e32 v239, 31, v238
	v_lshlrev_b64 v[238:239], 12, v[238:239]
	v_lshl_add_u64 v[238:239], v[4:5], 0, v[238:239]
	global_load_dwordx4 v[212:215], v[238:239], off
	s_mov_b64 exec, s[14:15]
	v_lshl_add_u32 v123, v241, 9, v78
	v_add_u32_e32 v241, 64, v6
	v_add_u32_e32 v240, s24, v241
	v_cmp_gt_u32_e32 vcc, s3, v240
	v_mov_b32_e32 v216, 0
	v_mov_b32_e32 v217, 0
	v_mov_b32_e32 v218, 0
	v_mov_b32_e32 v219, 0
	s_and_b64 exec, exec, vcc
	v_add_u32_e32 v236, s18, v240
	v_ashrrev_i32_e32 v237, 31, v236
	v_lshlrev_b64 v[236:237], 12, v[236:237]
	v_lshl_add_u64 v[236:237], v[4:5], 0, v[236:237]
	global_load_dwordx4 v[216:219], v[236:237], off
	s_mov_b64 exec, s[14:15]
	v_lshl_add_u32 v124, v241, 9, v78
	v_add_u32_e32 v241, 80, v6
	v_add_u32_e32 v240, s24, v241
	v_cmp_gt_u32_e32 vcc, s3, v240
	v_mov_b32_e32 v220, 0
	v_mov_b32_e32 v221, 0
	v_mov_b32_e32 v222, 0
	v_mov_b32_e32 v223, 0
	s_and_b64 exec, exec, vcc
	v_add_u32_e32 v238, s18, v240
	v_ashrrev_i32_e32 v239, 31, v238
	v_lshlrev_b64 v[238:239], 12, v[238:239]
	v_lshl_add_u64 v[238:239], v[4:5], 0, v[238:239]
	global_load_dwordx4 v[220:223], v[238:239], off
	s_mov_b64 exec, s[14:15]
	v_lshl_add_u32 v125, v241, 9, v78
	v_add_u32_e32 v241, 96, v6
	v_add_u32_e32 v240, s24, v241
	v_cmp_gt_u32_e32 vcc, s3, v240
	v_mov_b32_e32 v224, 0
	v_mov_b32_e32 v225, 0
	v_mov_b32_e32 v226, 0
	v_mov_b32_e32 v227, 0
	s_and_b64 exec, exec, vcc
	v_add_u32_e32 v236, s18, v240
	v_ashrrev_i32_e32 v237, 31, v236
	v_lshlrev_b64 v[236:237], 12, v[236:237]
	v_lshl_add_u64 v[236:237], v[4:5], 0, v[236:237]
	global_load_dwordx4 v[224:227], v[236:237], off
	s_mov_b64 exec, s[14:15]
	v_lshl_add_u32 v126, v241, 9, v78
	v_add_u32_e32 v241, 112, v6
	v_add_u32_e32 v240, s24, v241
	v_cmp_gt_u32_e32 vcc, s3, v240
	v_mov_b32_e32 v228, 0
	v_mov_b32_e32 v229, 0
	v_mov_b32_e32 v230, 0
	v_mov_b32_e32 v231, 0
	s_and_b64 exec, exec, vcc
	v_add_u32_e32 v238, s18, v240
	v_ashrrev_i32_e32 v239, 31, v238
	v_lshlrev_b64 v[238:239], 12, v[238:239]
	v_lshl_add_u64 v[238:239], v[4:5], 0, v[238:239]
	global_load_dwordx4 v[228:231], v[238:239], off
	s_mov_b64 exec, s[14:15]
	v_lshl_add_u32 v127, v241, 9, v78
	s_and_b64 exec, s[14:15], s[16:17]
	v_add_u32_e32 v241, 128, v6
	v_add_u32_e32 v240, s24, v241
	v_cmp_gt_u32_e32 vcc, s3, v240
	v_mov_b32_e32 v232, 0
	v_mov_b32_e32 v233, 0
	v_mov_b32_e32 v234, 0
	v_mov_b32_e32 v235, 0
	s_and_b64 exec, exec, vcc
	v_add_u32_e32 v236, s18, v240
	v_ashrrev_i32_e32 v237, 31, v236
	v_lshlrev_b64 v[236:237], 12, v[236:237]
	v_lshl_add_u64 v[236:237], v[4:5], 0, v[236:237]
	global_load_dwordx4 v[232:235], v[236:237], off
	s_mov_b64 exec, s[14:15]
	v_lshl_add_u32 v128, v241, 9, v78
	s_waitcnt vmcnt(0)
	ds_write_b128 v120, v[200:203]
	ds_write_b128 v121, v[204:207]
	ds_write_b128 v122, v[208:211]
	ds_write_b128 v123, v[212:215]
	ds_write_b128 v124, v[216:219]
	ds_write_b128 v125, v[220:223]
	ds_write_b128 v126, v[224:227]
	ds_write_b128 v127, v[228:231]
	s_and_b64 exec, s[14:15], s[16:17]
	ds_write_b128 v128, v[232:235]
	s_mov_b64 exec, s[14:15]
	v_mov_b32_e32 v0, s23
